# STEP2 epilogue: second row pair reuses the already scaled gate vectors (no reload), counted waits for that group
# speedup vs baseline: 1.0037x; 1.0037x over previous
;     __device__ __forceinline__ void operator()(const Acc& acc, const Unit& u, int wr, int wc, int fr, int fq) const {
;         const int col0 = u.pn * BM + wc * 32 + 4 * fq;
; #pragma unroll
;         for (int m = 0; m < 4; ++m) { const int kb = wr * 64 + m * 16 + fr;
; #pragma unroll
;             for (int bj = 0; bj < 2; ++bj)
; #pragma unroll
;                 for (int n = 0; n < 2; ++n) { const int q = col0 + bj * HALF + n * 16, ka = q >> 10, nn = q & 1023;
;                     const f32x4 g = *(const f32x4*)(gate + nn) * (1.f / 2048.f);
;                     const size_t o = (size_t)(ka + 128 * kb) * D + nn; *(f32x4*)(X + o) = *(const f32x4*)(Xin + o) + g * acc[0][bj][m][n]; }
;             if (m & 1) __builtin_amdgcn_sched_barrier(0); }
.Lgx_c_pre:
	s_ashr_i32 s8, s52, 2
	s_lshl_b32 s2, s52, 8
	v_add_u32_e32 v68, s8, v75
	s_and_b32 s2, s2, 0x300
	v_ashrrev_i32_e32 v69, 31, v68
	v_or_b32_e32 v81, s2, v79
	v_lshlrev_b64 v[72:73], 10, v[68:69]
	v_or_b32_e32 v82, v72, v81
	v_mov_b32_e32 v83, v73
	v_readlane_b32 s10, v253, 28
	v_lshlrev_b32_e32 v92, 2, v81
	v_lshlrev_b64 v[86:87], 2, v[82:83]
	v_readlane_b32 s11, v253, 29
	global_load_dwordx4 v[68:71], v92, s[92:93]
	s_mov_b32 s2, 0x3a000000
	v_lshl_add_u64 v[88:89], s[10:11], 0, v[86:87]
	global_load_dwordx4 v[140:143], v[88:89], off
	global_load_dwordx4 v[144:147], v[88:89], off offset:64
	global_load_dwordx4 v[148:151], v[88:89], off offset:512
	global_load_dwordx4 v[152:155], v[88:89], off offset:576
	v_mov_b32_e32 v91, v73
	s_waitcnt vmcnt(0)
	v_pk_mul_f32 v[68:69], v[68:69], s[2:3] op_sel_hi:[1,0]
	v_pk_mul_f32 v[70:71], v[70:71], s[2:3] op_sel_hi:[1,0]
	v_pk_fma_f32 v[62:63], v[62:63], v[68:69], v[140:141]
	v_pk_fma_f32 v[64:65], v[64:65], v[70:71], v[142:143]
	v_lshl_add_u64 v[82:83], s[22:23], 0, v[86:87]
	global_store_dwordx4 v[82:83], v[62:65], off
	v_or_b32_e32 v82, 16, v81
	v_lshlrev_b32_e32 v93, 2, v82
	global_load_dwordx4 v[62:65], v93, s[92:93]
	v_or_b32_e32 v90, v72, v82
	v_or_b32_e32 v83, 0x80, v81
	v_lshlrev_b32_e32 v94, 2, v83
	s_waitcnt vmcnt(0)
	v_pk_mul_f32 v[62:63], v[62:63], s[2:3] op_sel_hi:[1,0]
	v_pk_mul_f32 v[64:65], v[64:65], s[2:3] op_sel_hi:[1,0]
	v_pk_fma_f32 v[58:59], v[58:59], v[62:63], v[144:145]
	v_pk_fma_f32 v[60:61], v[60:61], v[64:65], v[146:147]
	v_lshl_add_u64 v[84:85], v[90:91], 2, s[22:23]
	global_store_dwordx4 v[84:85], v[58:61], off
	global_load_dwordx4 v[58:61], v94, s[92:93]
	v_or_b32_e32 v90, v72, v83
	s_waitcnt vmcnt(0)
	v_pk_mul_f32 v[58:59], v[58:59], s[2:3] op_sel_hi:[1,0]
	v_pk_mul_f32 v[60:61], v[60:61], s[2:3] op_sel_hi:[1,0]
	v_pk_fma_f32 v[54:55], v[54:55], v[58:59], v[148:149]
	v_pk_fma_f32 v[56:57], v[56:57], v[60:61], v[150:151]
	v_lshl_add_u64 v[84:85], v[90:91], 2, s[22:23]
	global_store_dwordx4 v[84:85], v[54:57], off
	s_nop 1
	v_or_b32_e32 v54, 0x90, v81
	v_lshlrev_b32_e32 v55, 2, v54
	global_load_dwordx4 v[84:87], v55, s[92:93]
	v_or_b32_e32 v72, v72, v54
	v_lshl_add_u64 v[72:73], v[72:73], 2, s[22:23]
	s_waitcnt vmcnt(0)
	v_pk_mul_f32 v[56:57], v[84:85], s[2:3] op_sel_hi:[1,0]
	v_pk_mul_f32 v[90:91], v[86:87], s[2:3] op_sel_hi:[1,0]
	s_waitcnt vmcnt(0)
	v_pk_fma_f32 v[52:53], v[52:53], v[90:91], v[154:155]
	v_pk_fma_f32 v[50:51], v[50:51], v[56:57], v[152:153]
	global_store_dwordx4 v[72:73], v[50:53], off
	s_nop 1
	v_add_u32_e32 v50, s8, v76
	v_ashrrev_i32_e32 v51, 31, v50
	v_lshlrev_b64 v[72:73], 10, v[50:51]
	v_or_b32_e32 v50, v72, v81
	v_mov_b32_e32 v51, v73
	v_lshlrev_b64 v[84:85], 2, v[50:51]
	v_lshl_add_u64 v[86:87], s[10:11], 0, v[84:85]
	global_load_dwordx4 v[140:143], v[86:87], off
	global_load_dwordx4 v[144:147], v[86:87], off offset:64
	global_load_dwordx4 v[148:151], v[86:87], off offset:512
	global_load_dwordx4 v[152:155], v[86:87], off offset:576
	s_waitcnt vmcnt(3)
	v_pk_fma_f32 v[48:49], v[48:49], v[70:71], v[142:143]
	v_pk_fma_f32 v[46:47], v[46:47], v[68:69], v[140:141]
	v_lshl_add_u64 v[50:51], s[22:23], 0, v[84:85]
	global_store_dwordx4 v[50:51], v[46:49], off
	v_or_b32_e32 v50, v72, v82
	v_mov_b32_e32 v51, v73
	s_waitcnt vmcnt(3)
	v_pk_fma_f32 v[44:45], v[44:45], v[64:65], v[146:147]
	v_pk_fma_f32 v[42:43], v[42:43], v[62:63], v[144:145]
	v_lshl_add_u64 v[46:47], v[50:51], 2, s[22:23]
	global_store_dwordx4 v[46:47], v[42:45], off
	v_or_b32_e32 v46, v72, v83
	v_mov_b32_e32 v47, v73
	v_or_b32_e32 v72, v72, v54
	s_waitcnt vmcnt(3)
	v_pk_fma_f32 v[40:41], v[40:41], v[60:61], v[150:151]
	v_pk_fma_f32 v[38:39], v[38:39], v[58:59], v[148:149]
	v_lshl_add_u64 v[42:43], v[46:47], 2, s[22:23]
	global_store_dwordx4 v[42:43], v[38:41], off
	s_waitcnt vmcnt(3)
;     __device__ __forceinline__ void operator()(const Acc& acc, const Unit& u, int wr, int wc, int fr, int fq) const {
;         const int col0 = u.pn * BM + wc * 32 + 4 * fq;
; #pragma unroll
;         for (int m = 0; m < 4; ++m) { const int kb = wr * 64 + m * 16 + fr;
; #pragma unroll
;             for (int bj = 0; bj < 2; ++bj)
; #pragma unroll
;                 for (int n = 0; n < 2; ++n) { const int q = col0 + bj * HALF + n * 16, ka = q >> 10, nn = q & 1023;
;                     const f32x4 g = *(const f32x4*)(gate + nn) * (1.f / 2048.f);
;                     const size_t o = (size_t)(ka + 128 * kb) * D + nn; *(f32x4*)(X + o) = *(const f32x4*)(Xin + o) + g * acc[0][bj][m][n]; }
;             if (m & 1) __builtin_amdgcn_sched_barrier(0); }
	v_pk_fma_f32 v[36:37], v[36:37], v[90:91], v[154:155]
	v_pk_fma_f32 v[34:35], v[34:35], v[56:57], v[152:153]
	v_lshl_add_u64 v[38:39], v[72:73], 2, s[22:23]
	global_store_dwordx4 v[38:39], v[34:37], off
	s_nop 1
	v_add_u32_e32 v34, s8, v77
	v_ashrrev_i32_e32 v35, 31, v34
	v_lshlrev_b64 v[42:43], 10, v[34:35]
	v_or_b32_e32 v38, v42, v81
	v_mov_b32_e32 v39, v43
	v_lshlrev_b64 v[44:45], 2, v[38:39]
	v_lshl_add_u64 v[46:47], s[10:11], 0, v[44:45]
	global_load_dwordx4 v[140:143], v[46:47], off
	global_load_dwordx4 v[144:147], v[46:47], off offset:64
	global_load_dwordx4 v[148:151], v[46:47], off offset:512
	global_load_dwordx4 v[152:155], v[46:47], off offset:576
	v_mov_b64_e32 v[34:35], v[68:69]
	v_mov_b64_e32 v[36:37], v[70:71]
	s_waitcnt vmcnt(3)
	v_pk_fma_f32 v[30:31], v[30:31], v[34:35], v[140:141]
	v_pk_fma_f32 v[32:33], v[32:33], v[36:37], v[142:143]
	v_lshl_add_u64 v[38:39], s[22:23], 0, v[44:45]
	global_store_dwordx4 v[38:39], v[30:33], off
	v_or_b32_e32 v44, v42, v82
	v_mov_b32_e32 v45, v43
	s_nop 0
	v_mov_b64_e32 v[30:31], v[62:63]
	v_mov_b64_e32 v[32:33], v[64:65]
	s_waitcnt vmcnt(3)
	v_pk_fma_f32 v[26:27], v[26:27], v[30:31], v[144:145]
	v_pk_fma_f32 v[28:29], v[28:29], v[32:33], v[146:147]
	v_lshl_add_u64 v[38:39], v[44:45], 2, s[22:23]
	global_store_dwordx4 v[38:39], v[26:29], off
	v_or_b32_e32 v44, v42, v83
	v_or_b32_e32 v42, v42, v54
	v_mov_b64_e32 v[38:39], v[58:59]
	v_mov_b64_e32 v[40:41], v[60:61]
	s_waitcnt vmcnt(3)
	v_pk_fma_f32 v[24:25], v[24:25], v[40:41], v[150:151]
	v_pk_fma_f32 v[22:23], v[22:23], v[38:39], v[148:149]
	v_lshl_add_u64 v[26:27], v[44:45], 2, s[22:23]
	global_store_dwordx4 v[26:27], v[22:25], off
	s_nop 1
	v_mov_b64_e32 v[26:27], v[56:57]
	v_mov_b64_e32 v[28:29], v[90:91]
	s_waitcnt vmcnt(3)
	v_pk_fma_f32 v[20:21], v[20:21], v[28:29], v[154:155]
	v_pk_fma_f32 v[18:19], v[18:19], v[26:27], v[152:153]
	v_lshl_add_u64 v[22:23], v[42:43], 2, s[22:23]
	global_store_dwordx4 v[22:23], v[18:21], off
	s_nop 1
	v_add_u32_e32 v18, s8, v78
	v_ashrrev_i32_e32 v19, 31, v18
	v_lshlrev_b64 v[22:23], 10, v[18:19]
	v_or_b32_e32 v18, v22, v81
	v_mov_b32_e32 v19, v23
	v_lshlrev_b64 v[24:25], 2, v[18:19]
	v_lshl_add_u64 v[42:43], s[10:11], 0, v[24:25]
	global_load_dwordx4 v[140:143], v[42:43], off
	global_load_dwordx4 v[144:147], v[42:43], off offset:64
	global_load_dwordx4 v[148:151], v[42:43], off offset:512
	global_load_dwordx4 v[152:155], v[42:43], off offset:576
	s_waitcnt vmcnt(3)
	v_pk_fma_f32 v[16:17], v[16:17], v[36:37], v[142:143]
	v_pk_fma_f32 v[14:15], v[14:15], v[34:35], v[140:141]
	v_lshl_add_u64 v[18:19], s[22:23], 0, v[24:25]
	global_store_dwordx4 v[18:19], v[14:17], off
	v_or_b32_e32 v18, v22, v82
	v_mov_b32_e32 v19, v23
	s_waitcnt vmcnt(3)
	v_pk_fma_f32 v[12:13], v[12:13], v[32:33], v[146:147]
	v_pk_fma_f32 v[10:11], v[10:11], v[30:31], v[144:145]
	v_lshl_add_u64 v[14:15], v[18:19], 2, s[22:23]
	global_store_dwordx4 v[14:15], v[10:13], off
	v_or_b32_e32 v14, v22, v83
	v_mov_b32_e32 v15, v23
	v_or_b32_e32 v22, v22, v54
	s_waitcnt vmcnt(3)
	v_pk_fma_f32 v[8:9], v[8:9], v[40:41], v[150:151]
	v_pk_fma_f32 v[6:7], v[6:7], v[38:39], v[148:149]
	v_lshl_add_u64 v[10:11], v[14:15], 2, s[22:23]
	global_store_dwordx4 v[10:11], v[6:9], off
	s_waitcnt vmcnt(3)
	v_pk_fma_f32 v[4:5], v[4:5], v[28:29], v[154:155]
	v_pk_fma_f32 v[2:3], v[2:3], v[26:27], v[152:153]
	v_lshl_add_u64 v[6:7], v[22:23], 2, s[22:23]
	global_store_dwordx4 v[6:7], v[2:5], off
	s_and_b64 vcc, exec, s[0:1]
	s_mov_b32 s52, s49
	s_mov_b64 s[10:11], s[6:7]
	s_mov_b64 s[8:9], s[4:5]
	s_cbranch_vccnz .Lgx_c_exit
	s_cmpk_gt_u32 s40, 0xff
	s_cbranch_scc0 .LBB0_934
	s_barrier
	s_branch .LBB0_934
